# attention phase: one static s_setprio 1 for waves 4..7 (second query half of every unit), reset at the phase end
# baseline (speedup 1.0000x reference)
.LBB0_782:
	s_and_b32 s5, s19, 0xe00
	s_add_i32 s16, s18, s5
	s_pack_ll_b32_b16 s5, s4, s4
	s_or_b32 s5, s5, 0x1c00180
	s_and_b32 s10, s5, 0xfff
	s_mulk_i32 s10, 0xaab
	s_lshr_b32 s10, s10, 20
	s_mulk_i32 s10, 0x180
	s_sub_i32 s10, s5, s10
	s_and_b32 s10, s10, 0xffff
	v_add_u32_e32 v1, s10, v120
	v_lshlrev_b32_e32 v28, 7, v1
	v_lshrrev_b32_e32 v1, 1, v1
	s_lshr_b32 s5, s5, 16
	v_xor_b32_e32 v1, v1, v115
	s_mul_i32 s17, s5, 0xaab
	v_lshlrev_b32_e32 v1, 4, v1
	s_lshr_b32 s17, s17, 20
	v_and_b32_e32 v1, 0x70, v1
	s_mulk_i32 s17, 0x180
	v_add3_u32 v1, 0, v28, v1
	s_sub_i32 s5, s5, s17
	s_waitcnt vmcnt(1)
	ds_write_b128 v1, v[22:25]
	v_or_b32_e32 v1, s10, v110
	s_and_b32 s5, s5, 0xffff
	v_lshlrev_b32_e32 v1, 1, v1
	v_add_u32_e32 v26, s5, v111
	v_add3_u32 v1, v121, v1, s21
	ds_write2_b64 v1, v[14:15], v[16:17] offset1:1
	v_lshrrev_b32_e32 v1, 1, v26
	v_xor_b32_e32 v1, v1, v115
	v_lshlrev_b32_e32 v1, 4, v1
	v_lshlrev_b32_e32 v27, 7, v26
	v_and_b32_e32 v1, 0x70, v1
	v_add3_u32 v1, 0, v27, v1
	s_addk_i32 s4, 0x200
	ds_write_b128 v1, v[18:21]
	v_or_b32_e32 v1, s5, v110
	s_and_b32 s5, s4, 0x1fff
	s_mulk_i32 s5, 0xaab
	s_lshr_b32 s5, s5, 20
	s_mulk_i32 s5, 0x180
	v_lshlrev_b32_e32 v1, 1, v1
	s_sub_i32 s4, s4, s5
	v_add3_u32 v1, v121, v1, s21
	s_and_b32 s4, s4, 0xffff
	ds_write2_b64 v1, v[10:11], v[12:13] offset1:1
	v_add_u32_e32 v1, s4, v108
	v_lshlrev_b32_e32 v10, 7, v1
	v_lshrrev_b32_e32 v1, 1, v1
	v_xor_b32_e32 v1, v1, v115
	v_lshlrev_b32_e32 v1, 4, v1
	v_and_b32_e32 v1, 0x70, v1
	v_add3_u32 v1, 0, v10, v1
	ds_write_b128 v1, v[6:9]
	v_or_b32_e32 v1, s4, v110
	s_lshl_b32 s4, s24, 2
	s_or_b32 s4, s4, s0
	s_lshl_b32 s10, s4, 7
	s_lshl_b32 s4, s4, 2
	v_lshlrev_b32_e32 v1, 1, v1
	v_or_b32_e32 v130, s14, v114
	s_add_u32 s14, s48, s4
	v_add3_u32 v1, v121, v1, s21
	v_mov_b32_e32 v131, s15
	v_lshl_add_u64 v[134:135], v[116:117], 0, s[10:11]
	s_addc_u32 s15, s49, 0
	v_lshl_add_u64 v[136:137], v[118:119], 0, s[10:11]
	s_waitcnt vmcnt(0)
	ds_write2_b64 v1, v[2:3], v[4:5] offset1:1
	s_waitcnt lgkmcnt(0)
	s_barrier
	s_add_i32 s10, s12, s1
	v_lshl_add_u64 v[186:187], v[130:131], 0, s[10:11]
	v_lshlrev_b64 v[186:187], 11, v[186:187]
	v_lshl_add_u64 v[186:187], v[186:187], 1, v[134:135]
	v_mov_b32_e32 v189, 0
	global_load_dwordx4 v[170:173], v[186:187], off nt
	global_load_dwordx4 v[174:177], v[186:187], off offset:32 nt
	global_load_dwordx4 v[178:181], v[186:187], off offset:64 nt
	global_load_dwordx4 v[182:185], v[186:187], off offset:96 nt
	global_load_dword v188, v189, s[14:15]
	s_waitcnt vmcnt(0)
	v_mul_f32_e32 v188, 0x3fb8aa3b, v188
	v_mbcnt_lo_u32_b32 v249, -1, 0
	v_mbcnt_hi_u32_b32 v249, -1, v249
	v_and_b32_e32 v251, 3, v249
	v_lshrrev_b32_e32 v250, 4, v249
	v_lshlrev_b32_e32 v250, 5, v250
	v_lshl_or_b32 v250, v251, 3, v250
	v_bfe_u32 v252, v249, 3, 1
	v_lshl_or_b32 v250, v252, 2, v250
	v_lshlrev_b32_e32 v251, 2, v251
	v_lshlrev_b32_e32 v249, 4, v249
	v_mov_b32_e32 v252, 0
	v_lshrrev_b32_e32 v254, 9, v249
	v_mul_u32_u24_e32 v254, 24, v254
	v_mov_b32_e32 v255, 0
	v_readlane_b32 s86, v248, 0
	s_lshr_b32 s86, s86, 6
	s_cmp_ge_u32 s86, 4
	s_cbranch_scc0 .Latt_noprio
	s_setprio 1
.Latt_noprio:
	s_lshl_b32 s94, s2, 3
	s_add_i32 s94, s94, s86
	s_and_b32 s86, s94, 1
	s_lshr_b32 s94, s94, 1
	v_readlane_b32 s74, v248, 16
	v_readlane_b32 s75, v248, 17
	s_lshl_b32 s95, s94, 13
	s_lshl_b32 s80, s86, 12
	s_add_i32 s95, s95, s80
	s_add_i32 s95, s95, 0x8000000
	s_add_u32 s74, s74, s95
	s_addc_u32 s75, s75, 0
	s_lshl_b32 s95, s86, 23
	s_lshl_b32 s80, s94, 7
	s_add_i32 s95, s95, s80
	s_add_i32 s95, s95, 0x14000000
	s_add_u32 s76, s54, s95
	s_addc_u32 s77, s55, 0
	s_lshl_b32 s95, s94, 3
	s_lshl_b32 s80, s86, 2
	s_add_i32 s95, s95, s80
	s_add_i32 s95, s95, 0xe0000
	s_add_u32 s78, s54, s95
	s_addc_u32 s79, s55, 0
	s_branch .LBB0_784

.LBB0_796:
	s_setprio 0
	s_cmp_gt_i32 s57, 12
	s_cselect_b64 s[4:5], -1, 0
	s_and_b64 s[0:1], s[6:7], s[4:5]
	s_andn2_b64 vcc, exec, s[0:1]
	s_cbranch_vccnz .LBB0_850
	s_waitcnt vmcnt(0)
	s_waitcnt vmcnt(0) lgkmcnt(0)
	s_barrier
	s_mov_b64 s[6:7], exec
	v_readlane_b32 s0, v248, 1
	v_readlane_b32 s1, v248, 2
	s_and_b64 s[0:1], s[6:7], s[0:1]
	s_mov_b64 exec, s[0:1]
	s_cbranch_execz .LBB0_849
	s_add_i32 s0, 0, 0x20020
	v_mov_b32_e32 v0, s0
	s_waitcnt vmcnt(0) expcnt(0) lgkmcnt(0)
	ds_read_b32 v2, v0
	s_add_i32 s0, 0, 0x20024
	v_mov_b32_e32 v0, s0
	ds_read_b32 v0, v0
	s_waitcnt lgkmcnt(1)
	v_cmp_ne_u32_e32 vcc, 0, v2
	s_cbranch_vccnz .LBB0_813
	s_add_u32 s8, s54, 0x4200
	s_addc_u32 s9, s55, 0
	s_add_u32 s10, s54, 0x4400
	s_addc_u32 s11, s55, 0
	s_add_u32 s12, s54, 0x4500
	s_addc_u32 s13, s55, 0
	s_add_u32 s14, s54, 0x4600
	s_addc_u32 s15, s55, 0
	s_add_u32 s16, s54, 0x4700
	s_addc_u32 s17, s55, 0
	s_add_u32 s18, s54, 0x4800
	s_addc_u32 s19, s55, 0
	s_add_u32 s20, s54, 0x4900
	s_addc_u32 s21, s55, 0
	s_add_u32 s22, s54, 0x4a00
	s_addc_u32 s23, s55, 0
	s_add_u32 s24, s54, 0x4b00
	s_addc_u32 s25, s55, 0
	s_add_u32 s26, s54, 0x4c00
	s_addc_u32 s27, s55, 0
	s_add_u32 s28, s54, 0x4d00
	s_addc_u32 s29, s55, 0
	s_add_u32 s30, s54, 0x4e00
	s_addc_u32 s31, s55, 0
	s_add_u32 s34, s54, 0x4f00
	s_addc_u32 s35, s55, 0
	s_add_u32 s36, s54, 0x5000
	s_addc_u32 s37, s55, 0
	s_add_u32 s44, s54, 0x5100
	s_addc_u32 s45, s55, 0
	s_add_u32 s46, s54, 0x5200
	s_addc_u32 s47, s55, 0
	s_mul_i32 s0, s59, s87
	s_add_u32 s48, s54, 0x5300
	s_mul_i32 s0, s0, s58
	s_addc_u32 s49, s55, 0
	s_mov_b32 s1, 1
	v_mov_b32_e32 v16, 0
	s_branch .LBB0_801
